# nt on all seven read-once f32 weight-copy streams + w_ada (adds the m4-phase copy of the next layer's ffn1 gate|up)
# baseline (speedup 1.0000x reference)
; #define LAS __attribute__((address_space(3)))
; __device__ __forceinline__ int launder(int x) { asm volatile("" : "+v"(x)); return x; }
; __device__ __forceinline__ int opaque_s(int x) { asm volatile("" : "+s"(x)); return x; }
; __device__ __forceinline__ const float* inp(int i) { const __attribute__((address_space(4))) Args* ka = (const __attribute__((address_space(4))) Args*)__builtin_amdgcn_kernarg_segment_ptr(); return ka->in[opaque_s(i)]; }
; __device__ __forceinline__ bf16* wsb(const Frame& F, size_t off) { return (bf16*)(F.ws + ((size_t)(unsigned)opaque_s((int)(off >> 20)) << 20)); }
; __device__ __forceinline__ void tr_load(const TrItem& t, f32x4 (&v)[16], int lane) {
;     const int c4 = 4 * (lane & 15), kq = lane >> 4; const bool okc = t.n0 + c4 < t.N;
; #pragma unroll
;     for (int i = 0; i < 16; ++i) { v[i] = (f32x4){0.f, 0.f, 0.f, 0.f}; if (okc) v[i] = *(const f32x4*)(t.W + (size_t)(t.k0 + 4 * i + kq) * t.N + t.n0 + c4); }
;     const int tid = launder(F.tid), lane = tid & 63, wave = __builtin_amdgcn_readfirstlane(tid >> 6), bid = opaque_s(F.bid);
;     if (bid < wg0) return;
;     LAS float* scr = (LAS float*)(F.lds + wave * 16640);
;     const int gw = (bid - wg0) * NWAVES + wave, NGW = (F.G - wg0) * NWAVES;
;     constexpr int I_GU = (D / 64) * (NGU / 64), I_DN = (DFF / 64) * (D / 64), I_IN = (D / 64) * ((INC + 63) / 64), I_OUT = (D / 64) * (D / 64);
;     const float* gu = inp(second ? I_GU2 : I_GU1) + (size_t)layer * D * NGU; const float* dn = inp(second ? I_D2 : I_D1) + (size_t)layer * DFF * D;
;     const float* sq = second ? inp(I_WOUT) + (size_t)layer * D * D : inp(I_WIN) + (size_t)layer * D * INC;
;     bf16* const pGU = wsb(F, second ? WS_WGU2 : WS_WGU1); bf16* const pDN = wsb(F, second ? WS_WD2 : WS_WD1); bf16* const pSQ = wsb(F, second ? WS_WOUT : WS_WIN);
;     const int nsq = second ? I_OUT : I_IN, nsqb = second ? D / 64 : (INC + 63) / 64, Nsq = second ? D : INC;
;     const int it0 = part == 2 || part == 5 ? I_GU : part == 4 ? I_GU / 2 : part == 6 ? I_GU + I_DN : 0;
;     const int it1 = part == 1 || part == 4 ? I_GU : part == 3 ? I_GU / 2 : part == 5 ? I_GU + I_DN : I_GU + I_DN + nsq;
;     ...
;     TrItem tc, tn; f32x4 vc[16], vn[16];
;     int it = it0 + gw;
;     if (it < it1) { TR_DESCRIBE(it, tc); tr_load(tc, vc, lane); }
.LBB0_1187:
	v_readlane_b32 s0, v253, 55
	v_readlane_b32 s1, v253, 56
	s_andn2_b64 vcc, exec, s[0:1]
	s_waitcnt vmcnt(0) lgkmcnt(0)
	s_barrier
	s_cbranch_vccnz .LBB0_1211
	v_mov_b32_e32 v4, v0
	s_mov_b32 s0, s60
	s_cmpk_lt_i32 s0, 0x88
	v_readfirstlane_b32 s1, v4
	s_cbranch_scc1 .LBB0_1211
	s_ashr_i32 s4, s1, 6
	s_lshl_b32 s0, s0, 3
	s_add_i32 s0, s4, s0
	s_add_i32 s12, s0, 0xfffffbc0
	s_mov_b32 s0, 7
	s_mov_b32 s1, 8
	s_mov_b32 s1, 11
	s_mov_b32 s92, 14
	s_mov_b32 s1, 58
	s_movk_i32 s1, 0x92
	s_cmpk_gt_i32 s12, 0x15ff
	s_cbranch_scc1 .LBB0_1210
	s_ashr_i32 s1, s0, 31
	s_lshl_b64 s[0:1], s[0:1], 3
	v_readlane_b32 s2, v252, 2
	v_readlane_b32 s3, v252, 3
	s_add_u32 s0, s2, s0
	s_addc_u32 s1, s3, s1
	s_load_dwordx2 s[0:1], s[0:1], 0x0
	v_readlane_b32 s2, v253, 50
	s_mul_i32 s2, s2, 0x5800000
	v_readlane_b32 s3, v253, 51
	s_mulk_i32 s4, 0x4100
	s_waitcnt lgkmcnt(0)
	s_add_u32 s0, s0, s2
	s_addc_u32 s1, s1, 0
	s_add_u32 s0, s0, 0x5800000
	s_addc_u32 s1, s1, 0
	s_lshl_b64 s[2:3], s[92:93], 20
	s_add_u32 s2, s78, s2
	s_addc_u32 s3, s79, s3
	s_add_i32 s5, s4, 0
	s_mul_hi_i32 s4, s12, 0x2e8ba2e9
	s_lshr_b32 s6, s4, 31
	s_ashr_i32 s4, s4, 5
	s_add_i32 s4, s4, s6
	s_mul_i32 s6, s4, 0xb0
	s_sub_i32 s7, s12, s6
	s_lshl_b32 s6, s7, 6
	s_cmpk_gt_i32 s7, 0x57
	s_cselect_b32 s7, 0xffffea00, 0
	s_cselect_b32 s8, 0x80, 0
	s_add_i32 s7, s7, s6
	s_lshl_b32 s7, s7, 1
	s_and_b32 s9, s6, 64
	s_and_b32 s7, s7, 0xffffff00
	s_or_b32 s8, s9, s8
	s_lshl_b32 s4, s4, 6
	v_bfe_u32 v135, v4, 4, 2
	s_or_b32 s13, s8, s7
	v_lshlrev_b32_e32 v2, 2, v4
	v_or_b32_e32 v5, s4, v135
	v_mov_b64_e32 v[6:7], s[0:1]
	s_mov_b32 s10, 0xb000
	s_ashr_i32 s7, s6, 31
	v_and_b32_e32 v134, 60, v2
	v_mad_i64_i32 v[8:9], s[8:9], v5, s10, v[6:7]
	s_lshl_b64 s[6:7], s[6:7], 2
	v_lshl_add_u64 v[8:9], v[8:9], 0, s[6:7]
	v_lshlrev_b32_e32 v2, 2, v134
	v_lshl_add_u64 v[8:9], v[8:9], 0, v[2:3]
	global_load_dwordx4 v[30:33], v[8:9], off nt
	v_or_b32_e32 v8, 4, v5
	v_mad_i64_i32 v[8:9], s[8:9], v8, s10, v[6:7]
	v_lshl_add_u64 v[8:9], v[8:9], 0, s[6:7]
	v_lshl_add_u64 v[8:9], v[8:9], 0, v[2:3]
	global_load_dwordx4 v[46:49], v[8:9], off nt
	v_or_b32_e32 v8, 8, v5
	v_mad_i64_i32 v[8:9], s[8:9], v8, s10, v[6:7]
	v_lshl_add_u64 v[8:9], v[8:9], 0, s[6:7]
	v_lshl_add_u64 v[8:9], v[8:9], 0, v[2:3]
	global_load_dwordx4 v[42:45], v[8:9], off nt
	v_or_b32_e32 v8, 12, v5
	v_mad_i64_i32 v[8:9], s[8:9], v8, s10, v[6:7]
	v_lshl_add_u64 v[8:9], v[8:9], 0, s[6:7]
	v_lshl_add_u64 v[8:9], v[8:9], 0, v[2:3]
	global_load_dwordx4 v[54:57], v[8:9], off nt
	v_or_b32_e32 v8, 16, v5
	v_mad_i64_i32 v[8:9], s[8:9], v8, s10, v[6:7]
	v_lshl_add_u64 v[8:9], v[8:9], 0, s[6:7]
	v_lshl_add_u64 v[8:9], v[8:9], 0, v[2:3]
	global_load_dwordx4 v[50:53], v[8:9], off nt
	v_or_b32_e32 v8, 20, v5
	v_mad_i64_i32 v[8:9], s[8:9], v8, s10, v[6:7]
	v_lshl_add_u64 v[8:9], v[8:9], 0, s[6:7]
	v_lshl_add_u64 v[8:9], v[8:9], 0, v[2:3]
	global_load_dwordx4 v[62:65], v[8:9], off nt
	v_or_b32_e32 v8, 24, v5
	v_mad_i64_i32 v[8:9], s[8:9], v8, s10, v[6:7]
	v_lshl_add_u64 v[8:9], v[8:9], 0, s[6:7]
	v_lshl_add_u64 v[8:9], v[8:9], 0, v[2:3]
	global_load_dwordx4 v[58:61], v[8:9], off nt
	v_or_b32_e32 v8, 28, v5
	v_mad_i64_i32 v[8:9], s[8:9], v8, s10, v[6:7]
	v_lshl_add_u64 v[8:9], v[8:9], 0, s[6:7]
	v_lshl_add_u64 v[8:9], v[8:9], 0, v[2:3]
	global_load_dwordx4 v[70:73], v[8:9], off nt
	v_or_b32_e32 v8, 32, v5
	v_mad_i64_i32 v[8:9], s[8:9], v8, s10, v[6:7]
	v_lshl_add_u64 v[8:9], v[8:9], 0, s[6:7]
	v_lshl_add_u64 v[8:9], v[8:9], 0, v[2:3]
	global_load_dwordx4 v[66:69], v[8:9], off nt
	v_or_b32_e32 v8, 36, v5
	v_mad_i64_i32 v[8:9], s[8:9], v8, s10, v[6:7]
	v_lshl_add_u64 v[8:9], v[8:9], 0, s[6:7]
	v_lshl_add_u64 v[8:9], v[8:9], 0, v[2:3]
	global_load_dwordx4 v[78:81], v[8:9], off nt
	v_or_b32_e32 v8, 40, v5
	v_mad_i64_i32 v[8:9], s[8:9], v8, s10, v[6:7]
	v_lshl_add_u64 v[8:9], v[8:9], 0, s[6:7]
	v_lshl_add_u64 v[8:9], v[8:9], 0, v[2:3]
	global_load_dwordx4 v[74:77], v[8:9], off nt
	v_or_b32_e32 v8, 44, v5
	v_mad_i64_i32 v[8:9], s[8:9], v8, s10, v[6:7]
	v_lshl_add_u64 v[8:9], v[8:9], 0, s[6:7]
	v_lshl_add_u64 v[8:9], v[8:9], 0, v[2:3]
	global_load_dwordx4 v[86:89], v[8:9], off nt
	v_or_b32_e32 v8, 48, v5
	v_mad_i64_i32 v[8:9], s[8:9], v8, s10, v[6:7]
	v_lshl_add_u64 v[8:9], v[8:9], 0, s[6:7]
	v_lshl_add_u64 v[8:9], v[8:9], 0, v[2:3]
	global_load_dwordx4 v[82:85], v[8:9], off nt
	v_or_b32_e32 v8, 52, v5
	v_mad_i64_i32 v[8:9], s[8:9], v8, s10, v[6:7]
	v_lshl_add_u64 v[8:9], v[8:9], 0, s[6:7]
	v_lshl_add_u64 v[8:9], v[8:9], 0, v[2:3]
	global_load_dwordx4 v[98:101], v[8:9], off nt
	v_or_b32_e32 v8, 56, v5
	v_or_b32_e32 v5, 60, v5
	v_mad_i64_i32 v[8:9], s[8:9], v8, s10, v[6:7]
	v_mad_i64_i32 v[6:7], s[8:9], v5, s10, v[6:7]
	v_lshl_add_u64 v[8:9], v[8:9], 0, s[6:7]
	v_lshl_add_u64 v[6:7], v[6:7], 0, s[6:7]
	v_lshl_add_u64 v[8:9], v[8:9], 0, v[2:3]
	v_lshl_add_u64 v[6:7], v[6:7], 0, v[2:3]
	global_load_dwordx4 v[110:113], v[8:9], off nt
	global_load_dwordx4 v[114:117], v[6:7], off nt
	v_add_u32_e32 v5, s5, v2
	v_lshlrev_b32_e32 v2, 3, v4
	v_bfe_u32 v140, v4, 3, 3
	v_and_b32_e32 v2, 56, v2
	v_mul_u32_u24_e32 v4, 0x104, v2
	v_lshlrev_b32_e32 v7, 2, v140
	v_readlane_b32 s6, v252, 62
	v_mul_u32_u24_e32 v6, 0x104, v135
	v_add3_u32 v141, s5, v4, v7
	s_add_i32 s5, s12, s6
	v_or_b32_e32 v142, 8, v140
	v_or_b32_e32 v143, 16, v140
	v_or_b32_e32 v144, 24, v140
	v_or_b32_e32 v145, 32, v140
	v_or_b32_e32 v146, 40, v140
	v_or_b32_e32 v147, 48, v140
	v_or_b32_e32 v148, 56, v140
	s_lshl_b32 s14, s5, 6
	s_lshl_b32 s15, s6, 6
	v_add_u32_e32 v149, v5, v6
	v_lshlrev_b32_e32 v136, 1, v2
	s_branch .LBB0_1193

; __device__ __forceinline__ void tr_load(const TrItem& t, f32x4 (&v)[16], int lane) {
;     const int c4 = 4 * (lane & 15), kq = lane >> 4; const bool okc = t.n0 + c4 < t.N;
; #pragma unroll
;     for (int i = 0; i < 16; ++i) { v[i] = (f32x4){0.f, 0.f, 0.f, 0.f}; if (okc) v[i] = *(const f32x4*)(t.W + (size_t)(t.k0 + 4 * i + kq) * t.N + t.n0 + c4); }
;     ...
;     TrItem tc, tn; f32x4 vc[16], vn[16];
;     int it = it0 + gw;
;     if (it < it1) { TR_DESCRIBE(it, tc); tr_load(tc, vc, lane); }
;     for (; it < it1; it += NGW) {
;         const bool more = it + NGW < it1;
;         if (more) { TR_DESCRIBE(it + NGW, tn); tr_load(tn, vn, lane); }
.LBB0_1193:
	s_waitcnt vmcnt(0)
	v_readlane_b32 s5, v252, 62
	s_add_i32 s12, s5, s12
	s_cmpk_gt_i32 s12, 0x15ff
	s_cselect_b64 s[6:7], -1, 0
	s_and_b64 vcc, exec, s[6:7]
	s_cbranch_vccnz .LBB0_1192
	s_mul_hi_i32 s5, s12, 0x2e8ba2e9
	s_lshr_b32 s8, s5, 31
	s_ashr_i32 s17, s5, 5
	s_add_i32 s17, s17, s8
	s_mul_i32 s5, s17, 0xffffd400
	s_add_i32 s8, s14, s5
	v_mov_b32_e32 v8, v3
	v_mov_b32_e32 v9, v3
	s_lshl_b32 s16, s17, 6
	v_add_u32_e32 v2, s8, v134
	s_movk_i32 s9, 0x2c00
	v_mov_b32_e32 v6, v3
	v_mov_b32_e32 v7, v3
	v_mov_b64_e32 v[12:13], v[8:9]
	v_mov_b64_e32 v[16:17], v[8:9]
	v_cmp_gt_i32_e32 vcc, s9, v2
	v_or_b32_e32 v137, s16, v135
	v_lshlrev_b32_e32 v138, 2, v134
	v_mov_b64_e32 v[10:11], v[6:7]
	v_mov_b64_e32 v[14:15], v[6:7]
	s_and_saveexec_b64 s[10:11], vcc
	s_mov_b32 s24, 0xb000
	s_cbranch_execz .LBB0_1196
	v_mov_b64_e32 v[4:5], s[0:1]
	v_mad_i64_i32 v[10:11], s[20:21], v137, s24, v[4:5]
	s_ashr_i32 s9, s8, 31
	s_lshl_b64 s[20:21], s[8:9], 2
	v_or_b32_e32 v2, 4, v137
	v_lshl_add_u64 v[10:11], v[10:11], 0, s[20:21]
	v_mov_b32_e32 v139, v3
	v_mad_i64_i32 v[4:5], s[22:23], v2, s24, v[4:5]
	v_lshl_add_u64 v[10:11], v[10:11], 0, v[138:139]
	v_lshl_add_u64 v[4:5], v[4:5], 0, s[20:21]
	v_lshl_add_u64 v[4:5], v[4:5], 0, v[138:139]
	global_load_dwordx4 v[14:17], v[10:11], off nt
	s_nop 0
	global_load_dwordx4 v[10:13], v[4:5], off nt
.LBB0_1196:
	s_or_b64 exec, exec, s[10:11]
	v_mov_b64_e32 v[20:21], v[8:9]
	v_mov_b64_e32 v[18:19], v[6:7]
	s_and_saveexec_b64 s[10:11], vcc
	s_cbranch_execz .LBB0_1198
	v_or_b32_e32 v2, 8, v137
	v_mov_b64_e32 v[4:5], s[0:1]
	v_mad_i64_i32 v[6:7], s[20:21], v2, s24, v[4:5]
	s_ashr_i32 s9, s8, 31
	s_lshl_b64 s[20:21], s[8:9], 2
	v_or_b32_e32 v2, 12, v137
	v_lshl_add_u64 v[6:7], v[6:7], 0, s[20:21]
	v_mov_b32_e32 v139, v3
	v_mad_i64_i32 v[4:5], s[22:23], v2, s24, v[4:5]
	v_lshl_add_u64 v[6:7], v[6:7], 0, v[138:139]
	v_lshl_add_u64 v[4:5], v[4:5], 0, s[20:21]
	v_lshl_add_u64 v[4:5], v[4:5], 0, v[138:139]
	global_load_dwordx4 v[18:21], v[6:7], off nt
	s_nop 0
	global_load_dwordx4 v[6:9], v[4:5], off nt
.LBB0_1198:
	s_or_b64 exec, exec, s[10:11]
	v_mov_b32_e32 v4, v3
	v_mov_b32_e32 v5, v3
	v_mov_b32_e32 v2, v3
	v_mov_b64_e32 v[24:25], v[4:5]
	v_mov_b64_e32 v[28:29], v[4:5]
	v_mov_b64_e32 v[22:23], v[2:3]
	v_mov_b64_e32 v[26:27], v[2:3]
	s_and_saveexec_b64 s[10:11], vcc
	s_cbranch_execz .LBB0_1200
	v_or_b32_e32 v24, 16, v137
	v_mov_b64_e32 v[22:23], s[0:1]
	v_mad_i64_i32 v[24:25], s[20:21], v24, s24, v[22:23]
	s_ashr_i32 s9, s8, 31
	v_or_b32_e32 v26, 20, v137
	s_lshl_b64 s[20:21], s[8:9], 2
	v_mad_i64_i32 v[22:23], s[22:23], v26, s24, v[22:23]
	v_lshl_add_u64 v[24:25], v[24:25], 0, s[20:21]
	v_mov_b32_e32 v139, v3
	v_lshl_add_u64 v[22:23], v[22:23], 0, s[20:21]
	v_lshl_add_u64 v[24:25], v[24:25], 0, v[138:139]
	v_lshl_add_u64 v[22:23], v[22:23], 0, v[138:139]
	global_load_dwordx4 v[26:29], v[24:25], off nt
	s_nop 0
	global_load_dwordx4 v[22:25], v[22:23], off nt
.LBB0_1200:
	s_or_b64 exec, exec, s[10:11]
	v_mov_b64_e32 v[36:37], v[4:5]
	v_mov_b64_e32 v[40:41], v[4:5]
	v_mov_b64_e32 v[34:35], v[2:3]
	v_mov_b64_e32 v[38:39], v[2:3]
	s_and_saveexec_b64 s[10:11], vcc
	s_cbranch_execz .LBB0_1202
	v_or_b32_e32 v2, 24, v137
	v_mov_b64_e32 v[4:5], s[0:1]
	v_mad_i64_i32 v[34:35], s[20:21], v2, s24, v[4:5]
	s_ashr_i32 s9, s8, 31
	s_lshl_b64 s[20:21], s[8:9], 2
	v_or_b32_e32 v2, 28, v137
	v_lshl_add_u64 v[34:35], v[34:35], 0, s[20:21]
	v_mov_b32_e32 v139, v3
	v_mad_i64_i32 v[4:5], s[22:23], v2, s24, v[4:5]
	v_lshl_add_u64 v[34:35], v[34:35], 0, v[138:139]
	v_lshl_add_u64 v[4:5], v[4:5], 0, s[20:21]
	v_lshl_add_u64 v[4:5], v[4:5], 0, v[138:139]
	global_load_dwordx4 v[38:41], v[34:35], off nt
	s_nop 0
	global_load_dwordx4 v[34:37], v[4:5], off nt
; __device__ __forceinline__ void tr_load(const TrItem& t, f32x4 (&v)[16], int lane) {
;     const int c4 = 4 * (lane & 15), kq = lane >> 4; const bool okc = t.n0 + c4 < t.N;
; #pragma unroll
;     for (int i = 0; i < 16; ++i) { v[i] = (f32x4){0.f, 0.f, 0.f, 0.f}; if (okc) v[i] = *(const f32x4*)(t.W + (size_t)(t.k0 + 4 * i + kq) * t.N + t.n0 + c4); }
;     ...
;     TrItem tc, tn; f32x4 vc[16], vn[16];
;     int it = it0 + gw;
;     if (it < it1) { TR_DESCRIBE(it, tc); tr_load(tc, vc, lane); }
;     for (; it < it1; it += NGW) {
;         const bool more = it + NGW < it1;
;         if (more) { TR_DESCRIBE(it + NGW, tn); tr_load(tn, vn, lane); }
.LBB0_1202:
	s_or_b64 exec, exec, s[10:11]
	v_mov_b32_e32 v4, v3
	v_mov_b32_e32 v5, v3
	v_mov_b32_e32 v2, v3
	v_mov_b64_e32 v[92:93], v[4:5]
	v_mov_b64_e32 v[96:97], v[4:5]
	v_mov_b64_e32 v[90:91], v[2:3]
	v_mov_b64_e32 v[94:95], v[2:3]
	s_and_saveexec_b64 s[10:11], vcc
	s_cbranch_execz .LBB0_1204
	v_or_b32_e32 v92, 32, v137
	v_mov_b64_e32 v[90:91], s[0:1]
	v_mad_i64_i32 v[92:93], s[20:21], v92, s24, v[90:91]
	s_ashr_i32 s9, s8, 31
	v_or_b32_e32 v94, 36, v137
	s_lshl_b64 s[20:21], s[8:9], 2
	v_mad_i64_i32 v[90:91], s[22:23], v94, s24, v[90:91]
	v_lshl_add_u64 v[92:93], v[92:93], 0, s[20:21]
	v_mov_b32_e32 v139, v3
	v_lshl_add_u64 v[90:91], v[90:91], 0, s[20:21]
	v_lshl_add_u64 v[92:93], v[92:93], 0, v[138:139]
	v_lshl_add_u64 v[90:91], v[90:91], 0, v[138:139]
	global_load_dwordx4 v[94:97], v[92:93], off nt
	s_nop 0
	global_load_dwordx4 v[90:93], v[90:91], off nt
.LBB0_1204:
	s_or_b64 exec, exec, s[10:11]
	v_mov_b64_e32 v[104:105], v[4:5]
	v_mov_b64_e32 v[108:109], v[4:5]
	v_mov_b64_e32 v[102:103], v[2:3]
	v_mov_b64_e32 v[106:107], v[2:3]
	s_and_saveexec_b64 s[10:11], vcc
	s_cbranch_execz .LBB0_1206
	v_or_b32_e32 v2, 40, v137
	v_mov_b64_e32 v[4:5], s[0:1]
	v_mad_i64_i32 v[102:103], s[20:21], v2, s24, v[4:5]
	s_ashr_i32 s9, s8, 31
	s_lshl_b64 s[20:21], s[8:9], 2
	v_or_b32_e32 v2, 44, v137
	v_lshl_add_u64 v[102:103], v[102:103], 0, s[20:21]
	v_mov_b32_e32 v139, v3
	v_mad_i64_i32 v[4:5], s[22:23], v2, s24, v[4:5]
	v_lshl_add_u64 v[102:103], v[102:103], 0, v[138:139]
	v_lshl_add_u64 v[4:5], v[4:5], 0, s[20:21]
	v_lshl_add_u64 v[4:5], v[4:5], 0, v[138:139]
	global_load_dwordx4 v[106:109], v[102:103], off nt
	s_nop 0
	global_load_dwordx4 v[102:105], v[4:5], off nt
.LBB0_1206:
	s_or_b64 exec, exec, s[10:11]
	v_mov_b32_e32 v4, v3
	v_mov_b32_e32 v5, v3
	v_mov_b32_e32 v2, v3
	v_mov_b64_e32 v[120:121], v[4:5]
	v_mov_b64_e32 v[124:125], v[4:5]
	v_mov_b64_e32 v[118:119], v[2:3]
	v_mov_b64_e32 v[122:123], v[2:3]
	s_and_saveexec_b64 s[10:11], vcc
	s_cbranch_execz .LBB0_1208
	v_or_b32_e32 v2, 48, v137
	v_mov_b64_e32 v[4:5], s[0:1]
	v_mad_i64_i32 v[118:119], s[20:21], v2, s24, v[4:5]
	s_ashr_i32 s9, s8, 31
	s_lshl_b64 s[20:21], s[8:9], 2
	v_or_b32_e32 v2, 52, v137
	v_lshl_add_u64 v[118:119], v[118:119], 0, s[20:21]
	v_mov_b32_e32 v139, v3
	v_mad_i64_i32 v[4:5], s[22:23], v2, s24, v[4:5]
	v_lshl_add_u64 v[118:119], v[118:119], 0, v[138:139]
	v_lshl_add_u64 v[4:5], v[4:5], 0, s[20:21]
	v_lshl_add_u64 v[4:5], v[4:5], 0, v[138:139]
	global_load_dwordx4 v[122:125], v[118:119], off nt
	s_nop 0
	global_load_dwordx4 v[118:121], v[4:5], off nt
.LBB0_1208:
	s_or_b64 exec, exec, s[10:11]
	s_mulk_i32 s17, 0xff50
	s_add_i32 s9, s12, s17
	s_cmpk_gt_i32 s9, 0x57
	s_cselect_b32 s19, 0xffffea00, 0
	s_cselect_b32 s17, 0x80, 0
	v_mov_b32_e32 v129, 0
	v_mov_b32_e32 v128, 0
	v_mov_b32_e32 v127, 0
	v_mov_b32_e32 v126, 0
	v_mov_b32_e32 v133, 0
	v_mov_b32_e32 v132, 0
	v_mov_b32_e32 v131, 0
	v_mov_b32_e32 v130, 0
	s_and_saveexec_b64 s[10:11], vcc
	s_cbranch_execz .LBB0_1191
	v_or_b32_e32 v2, 56, v137
	v_mov_b64_e32 v[4:5], s[0:1]
	v_mad_i64_i32 v[126:127], s[20:21], v2, s24, v[4:5]
	s_ashr_i32 s9, s8, 31
	s_lshl_b64 s[20:21], s[8:9], 2
	v_or_b32_e32 v2, 60, v137
	v_lshl_add_u64 v[126:127], v[126:127], 0, s[20:21]
	v_mov_b32_e32 v139, v3
	v_mad_i64_i32 v[4:5], s[22:23], v2, s24, v[4:5]
	v_lshl_add_u64 v[126:127], v[126:127], 0, v[138:139]
	v_lshl_add_u64 v[4:5], v[4:5], 0, s[20:21]
	v_lshl_add_u64 v[4:5], v[4:5], 0, v[138:139]
	global_load_dwordx4 v[126:129], v[126:127], off nt
	s_nop 0
	global_load_dwordx4 v[130:133], v[4:5], off nt
	s_branch .LBB0_1191
